# ff1 layer-0 GEMM k-loop: LDS-DMA source addresses from scalar bases + invariant lane offsets, m0 by SALU (removes 24 VALU ops per k-step)
# baseline (speedup 1.0000x reference)
.LBB0_1005:
	s_ashr_i32 s26, s31, 31
	s_lshr_b32 s26, s26, 29
	s_add_i32 s26, s31, s26
	s_ashr_i32 s27, s26, 3
	s_and_b32 s26, s26, -8
	s_sub_i32 s26, s31, s26
	s_cmp_lt_i32 s26, 0
	s_cselect_b32 s33, s29, 0x210
	s_mul_i32 s26, s33, s26
	s_add_i32 s35, s26, s27
	s_ashr_i32 s26, s35, 31
	s_lshr_b32 s26, s26, 24
	s_add_i32 s26, s35, s26
	s_ashr_i32 s27, s26, 8
	s_lshl_b32 s37, s27, 3
	s_and_b32 s36, s26, 0xffffff00
	s_sub_i32 s26, 0x84, s37
	s_min_u32 s38, s26, 8
	s_sub_i32 s34, s35, s36
	v_cvt_f32_ubyte0_e32 v1, s38
	v_cvt_f32_i32_e32 v0, s34
	v_rcp_iflag_f32_e32 v2, v1
	s_ashr_i32 s26, s34, 30
	s_or_b32 s33, s26, 1
	s_waitcnt lgkmcnt(0)
	v_mul_f32_e32 v2, v0, v2
	v_trunc_f32_e32 v2, v2
	v_fma_f32 v0, -v2, v1, v0
	v_cvt_i32_f32_e32 v2, v2
	v_cmp_ge_f32_e64 s[26:27], |v0|, v1
	s_and_b64 s[26:27], s[26:27], exec
	s_cselect_b32 s26, s33, 0
	v_readfirstlane_b32 s27, v2
	s_add_i32 s26, s27, s26
	s_mul_i32 s38, s26, s38
	s_sext_i32_i16 s33, s26
	s_sub_i32 s26, s34, s38
	s_sext_i32_i16 s26, s26
	s_add_i32 s34, s37, s26
	v_mad_i64_i32 v[0:1], s[26:27], s34, v85, v[66:67]
	v_mad_i64_i32 v[2:3], s[26:27], s33, v85, v[68:69]
	v_readfirstlane_b32 s26, v86
	s_mov_b32 m0, s26
	v_readfirstlane_b32 s26, v87
	s_barrier
	global_load_lds_dwordx4 v[0:1], off
	s_mov_b32 m0, s26
	v_readfirstlane_b32 s26, v88
	global_load_lds_dwordx4 v[2:3], off
	v_lshl_add_u64 v[4:5], v[0:1], 0, s[4:5]
	s_mov_b32 m0, s26
	v_readfirstlane_b32 s26, v89
	global_load_lds_dwordx4 v[4:5], off
	v_lshl_add_u64 v[4:5], v[2:3], 0, s[4:5]
	s_mov_b32 m0, s26
	v_readfirstlane_b32 s26, v90
	global_load_lds_dwordx4 v[4:5], off
	v_lshl_add_u64 v[4:5], v[0:1], 0, s[6:7]
	s_mov_b32 m0, s26
	v_readfirstlane_b32 s26, v91
	global_load_lds_dwordx4 v[4:5], off
	v_lshl_add_u64 v[4:5], v[2:3], 0, s[6:7]
	s_mov_b32 m0, s26
	v_readfirstlane_b32 s26, v92
	global_load_lds_dwordx4 v[4:5], off
	v_lshl_add_u64 v[0:1], v[0:1], 0, s[8:9]
	s_mov_b32 m0, s26
	v_readfirstlane_b32 s26, v93
	global_load_lds_dwordx4 v[0:1], off
	v_lshl_add_u64 v[0:1], v[2:3], 0, s[8:9]
	s_mov_b32 m0, s26
	s_sub_i32 s26, s35, s38
	global_load_lds_dwordx4 v[0:1], off
	s_sub_i32 s26, s26, s36
	s_sext_i32_i16 s26, s26
	s_add_i32 s37, s37, s26
	v_mad_i64_i32 v[74:75], s[26:27], s37, v85, v[70:71]
	v_mad_i64_i32 v[76:77], s[26:27], s33, v85, v[72:73]
	s_mov_b64 s[26:27], 0
	s_mov_b32 s35, 0
	v_mov_b32_e32 v20, 0
	v_mov_b32_e32 v21, v65
	v_mov_b32_e32 v22, v65
	v_mov_b32_e32 v23, v65
	v_mov_b32_e32 v0, 0
	v_mov_b32_e32 v1, v65
	v_mov_b32_e32 v2, v65
	v_mov_b32_e32 v3, v65
	v_mov_b32_e32 v4, 0
	v_mov_b32_e32 v5, v65
	v_mov_b32_e32 v6, v65
	v_mov_b32_e32 v7, v65
	v_mov_b32_e32 v8, 0
	v_mov_b32_e32 v9, v65
	v_mov_b32_e32 v10, v65
	v_mov_b32_e32 v11, v65
	v_mov_b32_e32 v12, 0
	v_mov_b32_e32 v13, v65
	v_mov_b32_e32 v14, v65
	v_mov_b32_e32 v15, v65
	v_mov_b32_e32 v16, 0
	v_mov_b32_e32 v17, v65
	v_mov_b32_e32 v18, v65
	v_mov_b32_e32 v19, v65
	v_mov_b32_e32 v24, 0
	v_mov_b32_e32 v25, v65
	v_mov_b32_e32 v26, v65
	v_mov_b32_e32 v27, v65
	v_mov_b32_e32 v28, 0
	v_mov_b32_e32 v29, v65
	v_mov_b32_e32 v30, v65
	v_mov_b32_e32 v31, v65
	v_mov_b32_e32 v32, 0
	v_mov_b32_e32 v33, v65
	v_mov_b32_e32 v34, v65
	v_mov_b32_e32 v35, v65
	v_mov_b32_e32 v36, 0
	v_mov_b32_e32 v37, v65
	v_mov_b32_e32 v38, v65
	v_mov_b32_e32 v39, v65
	v_mov_b32_e32 v40, 0
	v_mov_b32_e32 v41, v65
	v_mov_b32_e32 v42, v65
	v_mov_b32_e32 v43, v65
	v_mov_b32_e32 v44, 0
	v_mov_b32_e32 v45, v65
	v_mov_b32_e32 v46, v65
	v_mov_b32_e32 v47, v65
	v_mov_b32_e32 v48, 0
	v_mov_b32_e32 v49, v65
	v_mov_b32_e32 v50, v65
	v_mov_b32_e32 v51, v65
	v_mov_b32_e32 v52, 0
	v_mov_b32_e32 v53, v65
	v_mov_b32_e32 v54, v65
	v_mov_b32_e32 v55, v65
	v_mov_b32_e32 v56, 0
	v_mov_b32_e32 v57, v65
	v_mov_b32_e32 v58, v65
	v_mov_b32_e32 v59, v65
	v_mov_b32_e32 v60, 0
	v_mov_b32_e32 v61, v65
	v_mov_b32_e32 v62, v65
	v_mov_b32_e32 v63, v65
	v_readfirstlane_b32 s96, v74
	v_readfirstlane_b32 s97, v75
	v_readfirstlane_b32 s88, v76
	v_readfirstlane_b32 s89, v77
	v_readfirstlane_b32 s87, v78
	s_nop 1
	v_subrev_u32_e32 v244, s96, v74
	v_subrev_u32_e32 v245, s88, v76
	v_add_u32_e32 v246, 0x11000, v244
	v_add_u32_e32 v247, 0x11000, v245
	v_add_u32_e32 v248, 0x22000, v244
	v_add_u32_e32 v249, 0x22000, v245
	v_add_u32_e32 v250, 0x33000, v244
	v_add_u32_e32 v251, 0x33000, v245
	s_add_u32 s96, s96, 0x2200080
	s_addc_u32 s97, s97, 0
	s_add_u32 s88, s88, 0x1090080
	s_addc_u32 s89, s89, 0
.LBB0_1006:
	s_add_i32 s37, s35, 0x8000
	s_and_b32 s36, s37, 0x8000
	s_add_i32 s36, s36, 0
	s_add_u32 s86, s36, s87
	s_mov_b32 m0, s86
	s_waitcnt vmcnt(0) lgkmcnt(0)
	s_barrier
	global_load_lds_dwordx4 v244, s[96:97]
	s_add_u32 m0, s86, 0x4000
	s_nop 0
	global_load_lds_dwordx4 v245, s[88:89]
	s_add_u32 m0, s86, 0x1000
	s_nop 0
	global_load_lds_dwordx4 v246, s[96:97]
	s_add_u32 m0, s86, 0x5000
	s_nop 0
	global_load_lds_dwordx4 v247, s[88:89]
	s_add_u32 m0, s86, 0x2000
	s_nop 0
	global_load_lds_dwordx4 v248, s[96:97]
	s_add_u32 m0, s86, 0x6000
	s_nop 0
	global_load_lds_dwordx4 v249, s[88:89]
	s_add_u32 m0, s86, 0x3000
	s_nop 0
	global_load_lds_dwordx4 v250, s[96:97]
	s_add_u32 m0, s86, 0x7000
	s_nop 0
	global_load_lds_dwordx4 v251, s[88:89]
	s_add_u32 s96, s96, 0x80
	s_addc_u32 s97, s97, 0
	s_add_u32 s88, s88, 0x80
	s_addc_u32 s89, s89, 0
	s_and_b32 s35, s35, 0x8000
	s_add_i32 s35, s35, 0
	v_add_u32_e32 v134, s35, v80
	v_add3_u32 v110, s35, v81, v82
	v_add_u32_e32 v130, v134, v81
	ds_read_b128 v[94:97], v130 offset:16384
	ds_read_b128 v[98:101], v130 offset:18432
	ds_read_b128 v[102:105], v110
	ds_read_b128 v[106:109], v110 offset:2048
	ds_read_b128 v[110:113], v130 offset:20480
	ds_read_b128 v[114:117], v130 offset:22528
	ds_read_b128 v[118:121], v130 offset:24576
	ds_read_b128 v[122:125], v130 offset:26624
	ds_read_b128 v[126:129], v130 offset:28672
	ds_read_b128 v[130:133], v130 offset:30720
	s_waitcnt lgkmcnt(0)
	v_mfma_f32_16x16x32_bf16 v[52:55], v[110:113], v[102:105], v[52:55]
	v_add_u32_e32 v134, v134, v83
	s_add_u32 s26, s26, 0x80
	s_addc_u32 s27, s27, 0
	v_mfma_f32_16x16x32_bf16 v[16:19], v[110:113], v[106:109], v[16:19]
	v_add3_u32 v110, s35, v83, v82
	s_cmpk_eq_i32 s26, 0x780
	s_mov_b32 s35, s37
	v_mfma_f32_16x16x32_bf16 v[60:63], v[94:97], v[102:105], v[60:63]
	v_mfma_f32_16x16x32_bf16 v[56:59], v[98:101], v[102:105], v[56:59]
	v_mfma_f32_16x16x32_bf16 v[48:51], v[114:117], v[102:105], v[48:51]
	v_mfma_f32_16x16x32_bf16 v[44:47], v[118:121], v[102:105], v[44:47]
	v_mfma_f32_16x16x32_bf16 v[40:43], v[122:125], v[102:105], v[40:43]
	v_mfma_f32_16x16x32_bf16 v[36:39], v[126:129], v[102:105], v[36:39]
	v_mfma_f32_16x16x32_bf16 v[32:35], v[130:133], v[102:105], v[32:35]
	v_mfma_f32_16x16x32_bf16 v[28:31], v[94:97], v[106:109], v[28:31]
	v_mfma_f32_16x16x32_bf16 v[24:27], v[98:101], v[106:109], v[24:27]
	ds_read_b128 v[94:97], v134 offset:16384
	ds_read_b128 v[98:101], v134 offset:18432
	v_mfma_f32_16x16x32_bf16 v[12:15], v[114:117], v[106:109], v[12:15]
	v_mfma_f32_16x16x32_bf16 v[8:11], v[118:121], v[106:109], v[8:11]
	v_mfma_f32_16x16x32_bf16 v[4:7], v[122:125], v[106:109], v[4:7]
	v_mfma_f32_16x16x32_bf16 v[0:3], v[126:129], v[106:109], v[0:3]
	v_mfma_f32_16x16x32_bf16 v[20:23], v[130:133], v[106:109], v[20:23]
	ds_read_b128 v[102:105], v110
	ds_read_b128 v[106:109], v110 offset:2048
	ds_read_b128 v[110:113], v134 offset:20480
	ds_read_b128 v[114:117], v134 offset:22528
	ds_read_b128 v[118:121], v134 offset:24576
	ds_read_b128 v[122:125], v134 offset:26624
	ds_read_b128 v[126:129], v134 offset:28672
	ds_read_b128 v[130:133], v134 offset:30720
	s_waitcnt lgkmcnt(0)
	v_mfma_f32_16x16x32_bf16 v[60:63], v[94:97], v[102:105], v[60:63]
	v_mfma_f32_16x16x32_bf16 v[56:59], v[98:101], v[102:105], v[56:59]
	v_mfma_f32_16x16x32_bf16 v[52:55], v[110:113], v[102:105], v[52:55]
	v_mfma_f32_16x16x32_bf16 v[48:51], v[114:117], v[102:105], v[48:51]
	v_mfma_f32_16x16x32_bf16 v[44:47], v[118:121], v[102:105], v[44:47]
	v_mfma_f32_16x16x32_bf16 v[40:43], v[122:125], v[102:105], v[40:43]
	v_mfma_f32_16x16x32_bf16 v[36:39], v[126:129], v[102:105], v[36:39]
	v_mfma_f32_16x16x32_bf16 v[32:35], v[130:133], v[102:105], v[32:35]
	v_mfma_f32_16x16x32_bf16 v[28:31], v[94:97], v[106:109], v[28:31]
	v_mfma_f32_16x16x32_bf16 v[24:27], v[98:101], v[106:109], v[24:27]
	v_mfma_f32_16x16x32_bf16 v[16:19], v[110:113], v[106:109], v[16:19]
	v_mfma_f32_16x16x32_bf16 v[12:15], v[114:117], v[106:109], v[12:15]
	v_mfma_f32_16x16x32_bf16 v[8:11], v[118:121], v[106:109], v[8:11]
	v_mfma_f32_16x16x32_bf16 v[4:7], v[122:125], v[106:109], v[4:7]
	v_mfma_f32_16x16x32_bf16 v[0:3], v[126:129], v[106:109], v[0:3]
	v_mfma_f32_16x16x32_bf16 v[20:23], v[130:133], v[106:109], v[20:23]
	s_cbranch_scc0 .LBB0_1006
	v_add_u32_e32 v138, s36, v80
	v_add_u32_e32 v126, v138, v81
	s_waitcnt vmcnt(0)
	s_barrier
	ds_read_b128 v[74:77], v126 offset:16384
	v_add3_u32 v102, s36, v81, v82
	ds_read_b128 v[94:97], v102
	ds_read_b128 v[98:101], v126 offset:18432
	ds_read_b128 v[102:105], v102 offset:2048
	ds_read_b128 v[106:109], v126 offset:20480
	ds_read_b128 v[110:113], v126 offset:22528
	ds_read_b128 v[114:117], v126 offset:24576
	ds_read_b128 v[118:121], v126 offset:26624
	v_add3_u32 v134, s36, v83, v82
	v_add_u32_e32 v142, v138, v83
	ds_read_b128 v[122:125], v126 offset:28672
	ds_read_b128 v[126:129], v126 offset:30720
	ds_read_b128 v[130:133], v134
	ds_read_b128 v[134:137], v134 offset:2048
	ds_read_b128 v[138:141], v142 offset:16384
	ds_read_b128 v[146:149], v142 offset:18432
	s_waitcnt lgkmcnt(11)
	v_mfma_f32_16x16x32_bf16 v[56:59], v[98:101], v[94:97], v[56:59]
	s_lshl_b32 s36, s34, 7
	s_lshl_b32 s26, s33, 7
	s_ashr_i32 s27, s26, 31
	v_mfma_f32_16x16x32_bf16 v[60:63], v[74:77], v[94:97], v[60:63]
	s_lshl_b64 s[26:27], s[26:27], 1
	s_add_i32 s31, s31, s28
	s_cmpk_gt_i32 s31, 0x107f
	s_waitcnt lgkmcnt(0)
	v_mfma_f32_16x16x32_bf16 v[56:59], v[146:149], v[130:133], v[56:59]
	v_mfma_f32_16x16x32_bf16 v[48:51], v[110:113], v[94:97], v[48:51]
	v_mfma_f32_16x16x32_bf16 v[52:55], v[106:109], v[94:97], v[52:55]
	s_nop 5
	v_max_f32_e32 v56, v56, v56
	v_max_f32_e32 v57, v57, v57
	v_max_f32_e32 v56, 0, v56
	v_mfma_f32_16x16x32_bf16 v[44:47], v[114:117], v[94:97], v[44:47]
	v_max_f32_e32 v57, 0, v57
	v_max_f32_e32 v59, v59, v59
	v_max_f32_e32 v59, 0, v59
	v_mfma_f32_16x16x32_bf16 v[40:43], v[118:121], v[94:97], v[40:43]
	v_mfma_f32_16x16x32_bf16 v[36:39], v[122:125], v[94:97], v[36:39]
	v_mfma_f32_16x16x32_bf16 v[32:35], v[126:129], v[94:97], v[32:35]
	ds_read_b128 v[94:97], v142 offset:20480
	ds_read_b128 v[150:153], v142 offset:22528
	ds_read_b128 v[154:157], v142 offset:24576
	ds_read_b128 v[158:161], v142 offset:26624
	v_mfma_f32_16x16x32_bf16 v[60:63], v[138:141], v[130:133], v[60:63]
	s_waitcnt lgkmcnt(2)
	v_mfma_f32_16x16x32_bf16 v[48:51], v[150:153], v[130:133], v[48:51]
	v_mfma_f32_16x16x32_bf16 v[16:19], v[106:109], v[102:105], v[16:19]
	v_mul_f32_e64 v106, v56, v56
	v_mul_f32_e64 v107, v57, v57
	v_max_f32_e32 v57, v58, v58
	s_nop 1
	v_max_f32_e32 v60, v60, v60
	v_mfma_f32_16x16x32_bf16 v[24:27], v[98:101], v[102:105], v[24:27]
	v_add_u32_e32 v100, s36, v79
	v_mov_b64_e32 v[98:99], s[0:1]
	v_max_f32_e32 v61, v61, v61
	v_max_f32_e32 v56, v62, v62
	v_max_f32_e32 v58, 0, v57
	v_max_f32_e32 v57, v63, v63
	v_mad_i64_i32 v[100:101], s[34:35], v100, s30, v[98:99]
	v_max_f32_e32 v60, 0, v60
	v_max_f32_e32 v61, 0, v61
	v_max_f32_e32 v56, 0, v56
	v_max_f32_e32 v57, 0, v57
	v_mfma_f32_16x16x32_bf16 v[52:55], v[94:97], v[130:133], v[52:55]
	v_lshl_add_u64 v[100:101], v[100:101], 0, s[26:27]
	v_pk_mul_f32 v[60:61], v[60:61], v[60:61]
	v_pk_mul_f32 v[62:63], v[56:57], v[56:57]
	v_mfma_f32_16x16x32_bf16 v[28:31], v[74:77], v[102:105], v[28:31]
	v_max_f32_e32 v48, v48, v48
	v_max_f32_e32 v49, v49, v49
	ds_read_b128 v[74:77], v142 offset:28672
	ds_read_b128 v[162:165], v142 offset:30720
	v_mfma_f32_16x16x32_bf16 v[12:15], v[110:113], v[102:105], v[12:15]
	v_lshl_add_u64 v[100:101], v[100:101], 0, v[64:65]
	v_cvt_pk_bf16_f32 v56, v60, v61
	v_cvt_pk_bf16_f32 v57, v62, v63
	v_mfma_f32_16x16x32_bf16 v[8:11], v[114:117], v[102:105], v[8:11]
	v_max_f32_e32 v48, 0, v48
	v_max_f32_e32 v49, 0, v49
	v_max_f32_e32 v52, v52, v52
	v_mfma_f32_16x16x32_bf16 v[4:7], v[118:121], v[102:105], v[4:7]
	v_max_f32_e32 v53, v53, v53
	v_max_f32_e32 v51, v51, v51
	v_max_f32_e32 v52, 0, v52
	v_mfma_f32_16x16x32_bf16 v[0:3], v[122:125], v[102:105], v[0:3]
	v_max_f32_e32 v53, 0, v53
	v_max_f32_e32 v51, 0, v51
	v_pk_mul_f32 v[52:53], v[52:53], v[52:53]
	v_mfma_f32_16x16x32_bf16 v[20:23], v[126:129], v[102:105], v[20:23]
	v_mul_f32_e64 v102, v58, v58
	v_mul_f32_e64 v103, v59, v59
	v_cvt_pk_bf16_f32 v58, v106, v107
	v_cvt_pk_bf16_f32 v59, v102, v103
	s_waitcnt lgkmcnt(2)
	v_mfma_f32_16x16x32_bf16 v[40:43], v[158:161], v[130:133], v[40:43]
	global_store_dwordx4 v[100:101], v[56:59], off
	s_nop 1
	v_pk_mul_f32 v[56:57], v[48:49], v[48:49]
	v_max_f32_e32 v49, v50, v50
	v_max_f32_e32 v48, v54, v54
	v_max_f32_e32 v50, 0, v49
	v_max_f32_e32 v49, v55, v55
	v_mfma_f32_16x16x32_bf16 v[44:47], v[154:157], v[130:133], v[44:47]
	v_max_f32_e32 v48, 0, v48
	v_max_f32_e32 v49, 0, v49
	v_pk_mul_f32 v[54:55], v[48:49], v[48:49]
	v_pk_mul_f32 v[58:59], v[50:51], v[50:51]
	v_max_f32_e32 v40, v40, v40
	v_max_f32_e32 v41, v41, v41
	s_waitcnt lgkmcnt(0)
	v_mfma_f32_16x16x32_bf16 v[32:35], v[162:165], v[130:133], v[32:35]
	v_cvt_pk_bf16_f32 v48, v52, v53
	v_cvt_pk_bf16_f32 v49, v54, v55
	v_cvt_pk_bf16_f32 v50, v56, v57
	v_cvt_pk_bf16_f32 v51, v58, v59
	v_max_f32_e32 v40, 0, v40
	v_max_f32_e32 v41, 0, v41
	global_store_dwordx4 v[100:101], v[48:51], off offset:64
	v_max_f32_e32 v44, v44, v44
	v_max_f32_e32 v45, v45, v45
	v_pk_mul_f32 v[48:49], v[40:41], v[40:41]
	v_max_f32_e32 v41, v42, v42
	v_max_f32_e32 v40, v46, v46
	v_max_f32_e32 v42, 0, v41
	v_max_f32_e32 v41, v47, v47
	v_max_f32_e32 v43, v43, v43
	v_mfma_f32_16x16x32_bf16 v[36:39], v[74:77], v[130:133], v[36:39]
	v_max_f32_e32 v44, 0, v44
	v_max_f32_e32 v45, 0, v45
	v_max_f32_e32 v40, 0, v40
	v_max_f32_e32 v41, 0, v41
	v_max_f32_e32 v43, 0, v43
	v_pk_mul_f32 v[44:45], v[44:45], v[44:45]
	v_pk_mul_f32 v[46:47], v[40:41], v[40:41]
	v_pk_mul_f32 v[50:51], v[42:43], v[42:43]
	v_max_f32_e32 v32, v32, v32
	v_max_f32_e32 v33, v33, v33
	v_mfma_f32_16x16x32_bf16 v[24:27], v[146:149], v[134:137], v[24:27]
	v_cvt_pk_bf16_f32 v40, v44, v45
	v_cvt_pk_bf16_f32 v41, v46, v47
	v_cvt_pk_bf16_f32 v42, v48, v49
	v_cvt_pk_bf16_f32 v43, v50, v51
	v_max_f32_e32 v32, 0, v32
	v_max_f32_e32 v33, 0, v33
	global_store_dwordx4 v[100:101], v[40:43], off offset:128
	v_max_f32_e32 v36, v36, v36
	v_max_f32_e32 v37, v37, v37
	v_pk_mul_f32 v[40:41], v[32:33], v[32:33]
	v_max_f32_e32 v33, v34, v34
	v_max_f32_e32 v32, v38, v38
	v_max_f32_e32 v34, 0, v33
	v_max_f32_e32 v33, v39, v39
	v_max_f32_e32 v35, v35, v35
	v_mfma_f32_16x16x32_bf16 v[28:31], v[138:141], v[134:137], v[28:31]
	v_max_f32_e32 v36, 0, v36
	v_max_f32_e32 v37, 0, v37
	v_max_f32_e32 v32, 0, v32
	v_max_f32_e32 v33, 0, v33
	v_max_f32_e32 v35, 0, v35
	v_pk_mul_f32 v[36:37], v[36:37], v[36:37]
	v_pk_mul_f32 v[38:39], v[32:33], v[32:33]
	v_pk_mul_f32 v[42:43], v[34:35], v[34:35]
	v_max_f32_e32 v24, v24, v24
	v_max_f32_e32 v25, v25, v25
	v_mfma_f32_16x16x32_bf16 v[12:15], v[150:153], v[134:137], v[12:15]
	v_cvt_pk_bf16_f32 v32, v36, v37
	v_cvt_pk_bf16_f32 v33, v38, v39
	v_cvt_pk_bf16_f32 v34, v40, v41
	v_cvt_pk_bf16_f32 v35, v42, v43
	v_max_f32_e32 v24, 0, v24
	v_max_f32_e32 v25, 0, v25
	global_store_dwordx4 v[100:101], v[32:35], off offset:192
	v_max_f32_e32 v28, v28, v28
	v_max_f32_e32 v29, v29, v29
	v_pk_mul_f32 v[34:35], v[24:25], v[24:25]
	v_max_f32_e32 v25, v26, v26
	v_add_u32_e32 v32, s36, v84
	v_max_f32_e32 v24, v30, v30
	v_max_f32_e32 v26, 0, v25
	v_max_f32_e32 v25, v31, v31
	v_max_f32_e32 v27, v27, v27
	v_mfma_f32_16x16x32_bf16 v[16:19], v[94:97], v[134:137], v[16:19]
	v_mad_i64_i32 v[32:33], s[34:35], v32, s30, v[98:99]
	v_max_f32_e32 v28, 0, v28
	v_max_f32_e32 v29, 0, v29
	v_max_f32_e32 v24, 0, v24
	v_max_f32_e32 v25, 0, v25
	v_max_f32_e32 v27, 0, v27
	v_lshl_add_u64 v[32:33], v[32:33], 0, s[26:27]
	v_pk_mul_f32 v[28:29], v[28:29], v[28:29]
	v_pk_mul_f32 v[30:31], v[24:25], v[24:25]
	v_pk_mul_f32 v[36:37], v[26:27], v[26:27]
	v_max_f32_e32 v12, v12, v12
	v_max_f32_e32 v13, v13, v13
	v_mfma_f32_16x16x32_bf16 v[4:7], v[158:161], v[134:137], v[4:7]
	v_lshl_add_u64 v[32:33], v[32:33], 0, v[64:65]
	v_cvt_pk_bf16_f32 v24, v28, v29
	v_cvt_pk_bf16_f32 v25, v30, v31
	v_cvt_pk_bf16_f32 v26, v34, v35
	v_cvt_pk_bf16_f32 v27, v36, v37
	v_max_f32_e32 v12, 0, v12
	v_max_f32_e32 v13, 0, v13
	global_store_dwordx4 v[32:33], v[24:27], off
	v_max_f32_e32 v16, v16, v16
	v_max_f32_e32 v17, v17, v17
	v_pk_mul_f32 v[24:25], v[12:13], v[12:13]
	v_max_f32_e32 v13, v14, v14
	v_max_f32_e32 v12, v18, v18
	v_max_f32_e32 v14, 0, v13
	v_max_f32_e32 v13, v19, v19
	v_max_f32_e32 v15, v15, v15
	v_mfma_f32_16x16x32_bf16 v[8:11], v[154:157], v[134:137], v[8:11]
	v_max_f32_e32 v16, 0, v16
	v_max_f32_e32 v17, 0, v17
	v_max_f32_e32 v12, 0, v12
	v_max_f32_e32 v13, 0, v13
	v_max_f32_e32 v15, 0, v15
	v_pk_mul_f32 v[16:17], v[16:17], v[16:17]
	v_pk_mul_f32 v[18:19], v[12:13], v[12:13]
	v_pk_mul_f32 v[26:27], v[14:15], v[14:15]
	v_max_f32_e32 v4, v4, v4
	v_max_f32_e32 v5, v5, v5
	v_cvt_pk_bf16_f32 v12, v16, v17
	v_cvt_pk_bf16_f32 v13, v18, v19
	v_cvt_pk_bf16_f32 v14, v24, v25
	v_cvt_pk_bf16_f32 v15, v26, v27
	v_max_f32_e32 v4, 0, v4
	v_max_f32_e32 v5, 0, v5
	global_store_dwordx4 v[32:33], v[12:15], off offset:64
	v_mfma_f32_16x16x32_bf16 v[0:3], v[74:77], v[134:137], v[0:3]
	v_max_f32_e32 v8, v8, v8
	v_pk_mul_f32 v[12:13], v[4:5], v[4:5]
	v_max_f32_e32 v5, v6, v6
	v_mfma_f32_16x16x32_bf16 v[20:23], v[162:165], v[134:137], v[20:23]
	v_max_f32_e32 v9, v9, v9
	v_max_f32_e32 v4, v10, v10
	v_max_f32_e32 v6, 0, v5
	v_max_f32_e32 v5, v11, v11
	v_max_f32_e32 v7, v7, v7
	v_max_f32_e32 v8, 0, v8
	v_max_f32_e32 v9, 0, v9
	v_max_f32_e32 v4, 0, v4
	v_max_f32_e32 v5, 0, v5
	v_max_f32_e32 v7, 0, v7
	v_pk_mul_f32 v[8:9], v[8:9], v[8:9]
	v_pk_mul_f32 v[10:11], v[4:5], v[4:5]
	v_pk_mul_f32 v[14:15], v[6:7], v[6:7]
	v_cvt_pk_bf16_f32 v4, v8, v9
	v_cvt_pk_bf16_f32 v5, v10, v11
	v_cvt_pk_bf16_f32 v6, v12, v13
	v_cvt_pk_bf16_f32 v7, v14, v15
	global_store_dwordx4 v[32:33], v[4:7], off offset:128
	v_max_f32_e32 v0, v0, v0
	v_max_f32_e32 v1, v1, v1
	v_max_f32_e32 v4, v20, v20
	v_max_f32_e32 v5, v21, v21
	v_max_f32_e32 v2, v2, v2
	v_max_f32_e32 v6, v22, v22
	v_max_f32_e32 v3, v3, v3
	v_max_f32_e32 v7, v23, v23
	v_max_f32_e32 v0, 0, v0
	v_max_f32_e32 v4, 0, v4
	v_max_f32_e32 v1, 0, v1
	v_max_f32_e32 v5, 0, v5
	v_max_f32_e32 v2, 0, v2
	v_max_f32_e32 v6, 0, v6
	v_max_f32_e32 v3, 0, v3
	v_max_f32_e32 v7, 0, v7
	v_pk_mul_f32 v[0:1], v[0:1], v[0:1]
	v_pk_mul_f32 v[4:5], v[4:5], v[4:5]
	v_pk_mul_f32 v[2:3], v[2:3], v[2:3]
	v_pk_mul_f32 v[6:7], v[6:7], v[6:7]
	v_cvt_pk_bf16_f32 v0, v0, v1
	v_cvt_pk_bf16_f32 v1, v2, v3
	v_cvt_pk_bf16_f32 v2, v4, v5
	v_cvt_pk_bf16_f32 v3, v6, v7
	global_store_dwordx4 v[32:33], v[0:3], off offset:192
	s_cbranch_scc0 .LBB0_1005
